# MLA attention: static priority 1 for waves 4-7 during the tile loop
# speedup vs baseline: 1.0399x; 1.0008x over previous
; #define LAS __attribute__((address_space(3)))
; template <int TYPE>
; __device__ __forceinline__ void attn_item(const Params& p, int layer, int head, int qb, int mode, LAS unsigned char* lds) {
;     constexpr int DQK = TYPE == 0 ? 192 : 128, NQ = DQK / 16, SHM_K = 64 * DQK * 2;
;     constexpr int OFF_K = 2 * SHM_V, OFF_B = OFF_K + 2 * SHM_K;
;     const int tid = opaque_tid(), wid = __builtin_amdgcn_readfirstlane(tid >> 6), lane = tid & 63, r32 = lane & 31, hi = lane >> 5;
;     const int P0 = qb * 256, qrow = P0 + wid * 32 + r32;
;     const bf16_t* Qb; int ldq; const bf16_t* Kn; int ldk; const bf16_t* Vp; int ldv;
;     if (TYPE == 0) { Qb = (const bf16_t*)(p.ws + WS_QM) + head * 192; ldq = 1536; Kn = (const bf16_t*)(p.ws + WS_KV) + head * 256; ldk = 2048; Vp = Kn + 128; ldv = 2048; }
;     else { Qb = (const bf16_t*)(p.ws + WS_QF) + head * 128; ldq = 1024; Kn = (const bf16_t*)(p.ws + WS_KF) + head * 128; ldk = 1024; Vp = (const bf16_t*)(p.ws + WS_Z) + 3072 + head * 128; ldv = ZLD; }
;     const bf16_t* Krp = (const bf16_t*)(p.ws + WS_KR);
;     const float* bias = (const float*)(p.ws + WS_BK) + (size_t)head * MROWS;
;     ...
;     const int my_kmax = KMAX(qrow);
;     const int w_first = KMAX(P0 + wid * 32), w_last = KMAX(P0 + wid * 32 + 31);
;     int blk_kmax = KMAX(P0 + 255); if (blk_kmax > MROWS - 1) blk_kmax = MROWS - 1;
;     const int NT = blk_kmax / 64 + 1;
;     bf16x8 qr[NQ];
; #pragma unroll
;     for (int d0 = 0; d0 < NQ; ++d0) qr[d0] = *(const bf16x8*)(Qb + (size_t)qrow * ldq + d0 * 16 + hi * 8);
;     LAS unsigned char* V_lds = lds; LAS unsigned char* K_lds = lds + OFF_K; LAS float* B_lds = (LAS float*)(lds + OFF_B);
;     LAS float* wsl = (LAS float*)(lds + LDS_BYTES - 4096) + wid * 64;
;     const int vb0 = (int)(unsigned)(uintptr_t)V_lds + v_rd_base(lane);
;     unsigned offK[2], offV[2], offR;
; #pragma unroll
;     for (int j = 0; j < 2; ++j) {
; __device__ __forceinline__ void phase_attn(const Params& p, int layer, LAS unsigned char* lds) {
;     ...
;     for (;;) {
;         if (opaque_tid() == 0) *sitem = atomicAdd(ctr, 1);
;         __syncthreads();
;         const int it = *sitem;
;         __syncthreads();
;         if (it >= 464 + 264) break;
;         if (it < 264) attn_item<1>(p, layer, it & 7, 32 - (it >> 3), 0, lds);
;         else { const int e = MLA_ORDER[(it - 264) >> 3]; attn_item<0>(p, layer, it & 7, e & 63, e >> 6, lds); }
.LBB0_813:
	s_or_b64 exec, exec, s[0:1]
	v_readlane_b32 s0, v254, 10
	s_waitcnt vmcnt(0) lgkmcnt(0)
	s_barrier
	v_mov_b32_e32 v0, s0
	ds_read_b32 v0, v0
	s_movk_i32 s0, 0x2d7
	s_waitcnt lgkmcnt(0)
	s_barrier
	v_cmp_lt_i32_e32 vcc, s0, v0
	v_readfirstlane_b32 s42, v0
	s_mov_b64 s[0:1], -1
	s_cbranch_vccnz .LBB0_810
	s_cmpk_gt_i32 s42, 0x107
	s_cbranch_scc0 .LBB0_842
	s_add_i32 s0, s42, 0xfffffef8
	s_lshr_b32 s2, s0, 3
	s_getpc_b64 s[0:1]
	s_add_u32 s0, s0, MLA_ORDER@rel32@lo+4
	s_addc_u32 s1, s1, MLA_ORDER@rel32@hi+12
	v_mov_b32_e32 v0, s2
	global_load_sbyte v9, v0, s[0:1]
	v_mov_b32_e32 v2, v210
	s_and_b32 s5, s42, 7
	v_readfirstlane_b32 s6, v2
	s_ashr_i32 s13, s6, 6
	s_lshl_b32 s4, s13, 5
	s_mul_i32 s3, s5, 0x180
	v_and_b32_e32 v226, 31, v2
	v_and_b32_e32 v227, 63, v2
	v_lshlrev_b32_e32 v5, 3, v2
	v_bfe_u32 v225, v2, 5, 1
	v_bfe_u32 v223, v2, 4, 2
	v_and_b32_e32 v5, 24, v5
	s_movk_i32 s30, 0x60
	v_lshrrev_b32_e32 v6, 1, v2
	v_lshlrev_b32_e32 v0, 4, v225
	v_and_b32_e32 v224, 15, v2
	v_bfe_u32 v3, v2, 2, 2
	v_and_b32_e32 v4, 32, v2
	v_and_b32_e32 v6, 8, v6
	v_or_b32_e32 v13, v6, v3
	s_mov_b64 s[36:37], 0x100
	v_bfe_u32 v7, v2, 3, 3
	v_bitop3_b32 v8, v7, v2, 7 bitop3:0x78
	v_lshlrev_b32_e32 v7, 7, v7
	v_lshlrev_b32_e32 v8, 4, v8
	s_waitcnt vmcnt(0)
	v_readfirstlane_b32 s1, v9
	s_and_b32 s25, s1, 63
	s_lshl_b32 s2, s25, 8
	s_and_b32 s0, s1, 0xff
	s_bfe_u32 s24, s1, 0x20006
	s_add_i32 s2, s4, s2
	s_add_u32 s10, s21, s3
	v_readlane_b32 s3, v254, 60
	s_addc_u32 s11, s3, 0
	v_or_b32_e32 v9, s2, v226
	s_lshl_b32 s19, s5, 9
	v_readlane_b32 s3, v254, 61
	v_mov_b64_e32 v[10:11], s[10:11]
	s_movk_i32 s11, 0xc00
	s_add_u32 s7, s3, s19
	v_readlane_b32 s3, v254, 62
	v_mad_i64_i32 v[10:11], s[28:29], v9, s11, v[10:11]
	s_addc_u32 s10, s3, 0
	s_lshl_b32 s3, s25, 2
	s_and_b32 s28, s6, 0x3fffffc0
	s_lshl_b32 s14, s13, 1
	s_add_i32 s29, s13, 8
	s_lshl_b32 s12, s13, 2
	s_and_b32 s11, s6, 64
	s_add_i32 s6, s3, 4
	s_and_b32 s18, s14, 4
	s_lshl_b32 s3, s29, 2
	v_lshl_or_b32 v14, s29, 6, v227
	s_lshl_b32 s14, s29, 1
	s_lshl_b32 s28, s28, 2
	v_or_b32_e32 v12, s12, v223
	s_and_b32 s12, s12, 0xffff0
	v_or_b32_e32 v15, s3, v223
	v_and_or_b32 v14, v14, s30, v5
	s_and_b32 s30, s3, 0xffff0
	s_and_b32 s31, s14, 4
	s_add_i32 s3, s28, 0
	v_lshl_add_u64 v[10:11], v[10:11], 0, v[0:1]
	s_or_b32 s29, s12, s18
	s_or_b32 s14, s30, s31
	s_add_i32 s3, s3, 0x1f000
	v_or3_b32 v9, v4, s11, v5
	global_load_dwordx4 v[130:133], v[10:11], off
	global_load_dwordx4 v[134:137], v[10:11], off offset:32
	global_load_dwordx4 v[138:141], v[10:11], off offset:64
	global_load_dwordx4 v[142:145], v[10:11], off offset:96
	global_load_dwordx4 v[146:149], v[10:11], off offset:128
	global_load_dwordx4 v[150:153], v[10:11], off offset:160
	global_load_dwordx4 v[154:157], v[10:11], off offset:192
	global_load_dwordx4 v[158:161], v[10:11], off offset:224
	global_load_dwordx4 v[162:165], v[10:11], off offset:256
	global_load_dwordx4 v[166:169], v[10:11], off offset:288
	global_load_dwordx4 v[170:173], v[10:11], off offset:320
	global_load_dwordx4 v[174:177], v[10:11], off offset:352
	v_bitop3_b32 v10, v12, v224, 7 bitop3:0x6c
	s_cmp_lt_u32 s25, 33
	v_lshlrev_b32_e32 v11, 1, v9
	v_lshlrev_b32_e32 v9, 4, v10
	v_or_b32_e32 v10, s29, v13
	s_cselect_b32 s33, s6, 0x84
	v_lshl_or_b32 v17, v12, 12, v9
	v_lshl_or_b32 v12, v10, 12, v11
	v_or_b32_e32 v11, s14, v13
	s_add_i32 s14, s33, 4
	s_lshl_b32 s6, s13, 10
	s_lshr_b32 s14, s14, 1
	s_cmp_eq_u32 s24, 1
	s_sext_i32_i16 s1, s1
	s_cselect_b32 s40, s14, s33
	s_cmp_lt_i32 s1, 0
	s_cselect_b32 s14, s14, 3
	s_lshl_b64 s[38:39], s[14:15], 18
	s_add_u32 s28, s7, s38
	s_addc_u32 s29, s10, s39
	s_and_b32 s1, s14, 1
	s_mul_i32 s7, s1, 0x6000
	s_add_i32 s7, s7, 0
	s_lshl_b32 s1, s1, 13
	s_add_i32 s7, s7, s6
	v_mov_b32_e32 v13, v1
	v_bitop3_b32 v16, v15, v224, 7 bitop3:0x6c
	s_add_i32 m0, s7, 0x8000
	v_lshl_add_u64 v[12:13], s[28:29], 0, v[12:13]
	s_sub_i32 s1, s7, s1
	v_lshlrev_b32_e32 v10, 4, v16
	global_load_lds_dwordx4 v17, s[28:29]
	v_lshl_add_u64 v[12:13], v[12:13], 0, s[36:37]
	s_mov_b32 m0, s1
	v_lshlrev_b32_e32 v14, 1, v14
	v_lshl_or_b32 v15, v15, 12, v10
	global_load_lds_dwordx4 v[12:13], off
	s_add_i32 m0, s7, 0xa000
	v_lshl_or_b32 v14, v11, 12, v14
	global_load_lds_dwordx4 v15, s[28:29]
	v_mov_b32_e32 v15, v1
	s_add_i32 m0, s1, 0x2000
	v_lshl_add_u64 v[12:13], s[28:29], 0, v[14:15]
	s_cmp_gt_u32 s0, 63
	v_lshl_add_u64 v[12:13], v[12:13], 0, s[36:37]
	s_cselect_b64 s[36:37], -1, 0
	s_cmp_lt_u32 s0, 64
	s_cselect_b32 s7, s33, s40
	s_lshl_b64 s[40:41], s[14:15], 13
	v_readlane_b32 s0, v254, 63
	s_add_u32 s0, s0, s40
	v_readlane_b32 s1, v255, 0
	s_addc_u32 s1, s1, s41
	s_bitcmp1_b32 s14, 0
	s_cselect_b32 s10, 0x6000, 0
	s_add_i32 s10, s10, 0
	s_add_i32 s10, s10, s6
	v_or3_b32 v11, v8, v7, s6
	global_load_lds_dwordx4 v[12:13], off
	s_add_i32 m0, s10, 0xc000
	s_sub_i32 s7, s7, s14
	global_load_lds_dwordx4 v11, s[0:1]
	s_waitcnt vmcnt(0)
	s_cmp_lt_i32 s7, 1
	v_cmp_gt_u32_e64 s[0:1], 32, v227
	s_waitcnt vmcnt(0) lgkmcnt(0)
	s_barrier
; #define LAS __attribute__((address_space(3)))
; template <int TYPE>
; __device__ __forceinline__ void attn_item(const Params& p, int layer, int head, int qb, int mode, LAS unsigned char* lds) {
;     ...
;     float m_reg = -1e30f, l_reg = 0.f; f32x16 o[4];
; #pragma unroll
;     for (int d = 0; d < 4; ++d) o[d] = (f32x16){};
;     constexpr int T0 = PADR / 64;
;     int tbeg = T0; float Bb = 0.f;
;     if (TYPE == 1) {
;         const float* gq = p.in[I_GFQ] + layer * 128; const float* gk = p.in[I_GFK] + layer * 128;
;         float gm = fmaxf(fabsf(gq[lane] * gk[lane]), fabsf(gq[lane + 64] * gk[lane + 64]));
; #pragma unroll
;         for (int o_ = 32; o_ >= 1; o_ >>= 1) gm = fmaxf(gm, __shfl_xor(gm, o_));
;         Bb = gm * 11.313708498984761f * LOG2E * 1.02f;
;     }
;     int tend = NT;
;     if (TYPE == 0 && mode != 0) { const int mid = (T0 + NT + 1) >> 1; if (mode == 1) tend = mid; else tbeg = mid; }
;     const int ntiles = tend - tbeg, tfirst = TYPE == 1 ? tend - 1 : tbeg;
;     LAS float* xm = (LAS float*)(lds + LDS_BYTES - 2048);
;     ADMA(tfirst, tfirst & 1);
;     asm volatile("s_waitcnt vmcnt(0)" ::: "memory");
;     __syncthreads();
;     int kb[4], kbr[4];
; #pragma unroll
;     for (int dd = 0; dd < 4; ++dd) { kb[dd] = r32 * 256 + ((((dd * 2 + hi) ^ (r32 & 7))) << 4); kbr[dd] = 16384 + r32 * 128 + ((((dd * 2 + hi) ^ (r32 & 7))) << 4); }
	s_cbranch_scc1 .LBB0_830
	v_lshlrev_b32_e32 v13, 4, v227
	v_lshlrev_b32_e32 v12, 3, v227
	v_and_b32_e32 v13, 0xc0, v13
	v_lshlrev_b32_e32 v14, 1, v227
	v_and_b32_e32 v11, 7, v2
	v_and_or_b32 v13, v12, 24, v13
	v_and_b32_e32 v14, 32, v14
	v_and_b32_e32 v12, 0x100, v12
	v_or3_b32 v12, v13, v14, v12
	v_xor_b32_e32 v13, v225, v11
	s_or_b32 s10, s2, 63
	v_lshlrev_b32_e32 v230, 4, v13
	v_bitop3_b32 v13, v225, v11, 2 bitop3:0x36
	v_lshlrev_b32_e32 v231, 4, v13
	v_bitop3_b32 v13, v225, v11, 4 bitop3:0x36
	s_add_u32 s28, s40, 0x27d62000
	v_lshlrev_b32_e32 v232, 4, v13
	v_add_u32_e32 v234, 0, v12
	s_addc_u32 s29, s41, 0
	v_add3_u32 v12, s6, v7, v8
	v_mov_b32_e32 v13, v1
	s_or_b32 s19, s38, s19
	v_lshl_add_u64 v[200:201], s[28:29], 0, v[12:13]
	s_add_u32 s28, s19, 0x25ca0100
	s_addc_u32 s29, s39, 0
	s_add_i32 s31, s31, s30
	s_lshl_b32 s30, s13, 6
	s_addk_i32 s30, 0x200
	v_or_b32_e32 v8, s30, v227
	v_add_u32_e32 v7, s31, v6
	v_lshlrev_b32_e32 v8, 1, v8
	v_and_b32_e32 v2, 3, v2
	v_add_lshl_u32 v7, v7, v3, 12
	v_and_b32_e32 v8, 0xc0, v8
	v_lshlrev_b32_e32 v2, 4, v2
	s_add_i32 s18, s18, s12
	v_or3_b32 v12, v7, v8, v2
	v_add3_u32 v2, s18, v6, v3
	v_add_u32_e32 v3, s11, v4
	s_add_u32 s18, s19, 0x25ca0000
	v_add_lshl_u32 v3, v3, v5, 1
	s_addc_u32 s19, s39, 0
	s_lshl_b32 s11, s13, 14
	v_lshl_or_b32 v2, v2, 12, v3
	v_mov_b32_e32 v3, v1
	s_add_i32 s12, s11, 0x20000
	v_lshlrev_b32_e32 v4, 12, v223
	v_lshl_add_u64 v[204:205], s[28:29], 0, v[2:3]
	v_or3_b32 v2, s12, v4, v10
	v_bitop3_b32 v11, v225, v11, 6 bitop3:0x36
	v_lshl_add_u64 v[206:207], s[18:19], 0, v[2:3]
	v_or3_b32 v2, s11, v4, v9
	v_mov_b32_e32 v16, v1
	v_mov_b32_e32 v17, v1
	v_lshlrev_b32_e32 v233, 4, v11
	v_lshl_add_u64 v[202:203], s[28:29], 0, v[12:13]
	v_lshl_add_u64 v[208:209], s[18:19], 0, v[2:3]
	v_mov_b32_e32 v2, v1
	v_mov_b32_e32 v4, v1
	v_mov_b32_e32 v5, v1
	v_mov_b32_e32 v6, v1
	v_mov_b32_e32 v7, v1
	v_mov_b32_e32 v8, v1
	v_mov_b32_e32 v9, v1
	v_mov_b32_e32 v10, v1
	v_mov_b32_e32 v11, v1
	v_mov_b32_e32 v12, v1
	v_mov_b32_e32 v14, v1
	v_mov_b32_e32 v15, v1
	v_mov_b64_e32 v[64:65], v[16:17]
	v_mov_b64_e32 v[48:49], v[16:17]
	v_mov_b64_e32 v[32:33], v[16:17]
	v_lshlrev_b32_e32 v228, 8, v226
	v_lshlrev_b32_e32 v229, 7, v226
	v_lshl_add_u32 v235, v226, 2, s3
	s_lshl_b32 s11, s14, 6
	s_mov_b32 s12, 0
	v_mov_b32_e32 v199, 0
	v_mov_b32_e32 v198, 0xf149f2ca
	v_add_u32_e32 v0, s3, v0
	v_mov_b64_e32 v[62:63], v[14:15]
	v_mov_b64_e32 v[60:61], v[12:13]
	v_mov_b64_e32 v[58:59], v[10:11]
	v_mov_b64_e32 v[56:57], v[8:9]
	v_mov_b64_e32 v[54:55], v[6:7]
	v_mov_b64_e32 v[52:53], v[4:5]
	v_mov_b64_e32 v[50:51], v[2:3]
	v_mov_b64_e32 v[46:47], v[14:15]
	v_mov_b64_e32 v[44:45], v[12:13]
	v_mov_b64_e32 v[42:43], v[10:11]
	v_mov_b64_e32 v[40:41], v[8:9]
	v_mov_b64_e32 v[38:39], v[6:7]
	v_mov_b64_e32 v[36:37], v[4:5]
	v_mov_b64_e32 v[34:35], v[2:3]
	v_mov_b64_e32 v[30:31], v[14:15]
	v_mov_b64_e32 v[28:29], v[12:13]
	v_mov_b64_e32 v[26:27], v[10:11]
	v_mov_b64_e32 v[24:25], v[8:9]
	v_mov_b64_e32 v[22:23], v[6:7]
	v_mov_b64_e32 v[20:21], v[4:5]
	v_mov_b64_e32 v[18:19], v[2:3]
	v_readlane_b32 s31, v254, 57
	v_readlane_b32 s30, v254, 23
	v_readfirstlane_b32 s100, v210
	s_bitcmp1_b32 s100, 8
	s_cbranch_scc0 .Lmp_noprio
	s_setprio 1

; __device__ __forceinline__ int crow(int r, int hi) { return (r & 3) + 8 * (r >> 2) + 4 * hi; }
; template <int TYPE>
; __device__ __forceinline__ void attn_item(const Params& p, int layer, int head, int qb, int mode, LAS unsigned char* lds) {
;     ...
;     if (TYPE == 0 && mode != 0) {
;         const int pi = (head * 25 + (qb - 8)) * 2 + (mode - 1);
;         float* Op = (float*)(p.ws + WS_U) + (size_t)pi * (256 * 128) + (size_t)(wid * 32) * 128;
;         float* ML = (float*)(p.ws + WS_U) + (size_t)400 * (256 * 128) + (size_t)pi * 512 + (wid * 32 + r32) * 2;
; #pragma unroll
;         for (int r = 0; r < 16; ++r)
; #pragma unroll
;             for (int d0 = 0; d0 < 4; ++d0) Op[crow(r, hi) * 128 + d0 * 32 + r32] = o[d0][r];
;         if (hi == 0) { ML[0] = m_reg; ML[1] = l_reg; }
;         __syncthreads();
.LBB0_831:
	s_setprio 0
	s_lshl_b32 s6, s5, 8
	s_mov_b64 s[0:1], -1
	s_and_b64 vcc, exec, s[36:37]
	s_cbranch_vccz .LBB0_835
	s_mul_i32 s0, s5, 25
	s_add_i32 s0, s0, s25
	s_lshl_b32 s0, s0, 1
	s_add_i32 s0, s0, s24
	s_sub_i32 s0, s0, 17
	s_ashr_i32 s1, s0, 31
	s_lshl_b64 s[10:11], s[0:1], 17
	s_add_u32 s7, s44, s10
	s_addc_u32 s12, s45, s11
	s_ashr_i32 s5, s4, 31
	s_lshl_b64 s[10:11], s[4:5], 9
	s_add_u32 s10, s7, s10
	v_lshlrev_b32_e32 v0, 2, v226
	s_addc_u32 s11, s12, s11
	v_lshl_or_b32 v0, v225, 11, v0
	v_lshl_add_u64 v[66:67], s[10:11], 0, v[0:1]
	s_movk_i32 s5, 0x1000
	v_add_co_u32_e32 v68, vcc, s5, v66
	s_movk_i32 s5, 0x2000
	s_nop 0
	v_addc_co_u32_e32 v69, vcc, 0, v67, vcc
	v_add_co_u32_e32 v70, vcc, s5, v66
	s_movk_i32 s5, 0x3000
	s_nop 0
	v_addc_co_u32_e32 v71, vcc, 0, v67, vcc
	v_add_co_u32_e32 v66, vcc, s5, v66
	global_store_dword v0, v2, s[10:11]
	global_store_dword v0, v50, s[10:11] offset:128
	global_store_dword v0, v34, s[10:11] offset:256
	global_store_dword v0, v18, s[10:11] offset:384
	global_store_dword v0, v3, s[10:11] offset:512
	global_store_dword v0, v51, s[10:11] offset:640
	global_store_dword v0, v35, s[10:11] offset:768
	global_store_dword v0, v19, s[10:11] offset:896
	global_store_dword v0, v4, s[10:11] offset:1024
	global_store_dword v0, v52, s[10:11] offset:1152
	global_store_dword v0, v36, s[10:11] offset:1280
	global_store_dword v0, v20, s[10:11] offset:1408
	global_store_dword v0, v5, s[10:11] offset:1536
	global_store_dword v0, v53, s[10:11] offset:1664
	global_store_dword v0, v37, s[10:11] offset:1792
	global_store_dword v0, v21, s[10:11] offset:1920
	v_addc_co_u32_e32 v67, vcc, 0, v67, vcc
	v_cmp_gt_u32_e32 vcc, 32, v227
	global_store_dword v[70:71], v6, off offset:-4096
	global_store_dword v[68:69], v54, off offset:128
	global_store_dword v[68:69], v38, off offset:256
	global_store_dword v[68:69], v22, off offset:384
	global_store_dword v[68:69], v7, off offset:512
	global_store_dword v[68:69], v55, off offset:640
	global_store_dword v[68:69], v39, off offset:768
	global_store_dword v[68:69], v23, off offset:896
	global_store_dword v[68:69], v8, off offset:1024
	global_store_dword v[68:69], v56, off offset:1152
	global_store_dword v[68:69], v40, off offset:1280
	global_store_dword v[68:69], v24, off offset:1408
	global_store_dword v[68:69], v9, off offset:1536
	global_store_dword v[68:69], v57, off offset:1664
	global_store_dword v[68:69], v41, off offset:1792
	global_store_dword v[68:69], v25, off offset:1920
	global_store_dword v[70:71], v10, off
	global_store_dword v[70:71], v58, off offset:128
	global_store_dword v[70:71], v42, off offset:256
	global_store_dword v[70:71], v26, off offset:384
	global_store_dword v[70:71], v11, off offset:512
	global_store_dword v[70:71], v59, off offset:640
	global_store_dword v[70:71], v43, off offset:768
	global_store_dword v[70:71], v27, off offset:896
	global_store_dword v[70:71], v12, off offset:1024
	global_store_dword v[70:71], v60, off offset:1152
	global_store_dword v[70:71], v44, off offset:1280
	global_store_dword v[70:71], v28, off offset:1408
	global_store_dword v[70:71], v13, off offset:1536
	global_store_dword v[70:71], v61, off offset:1664
	global_store_dword v[70:71], v45, off offset:1792
	global_store_dword v[70:71], v29, off offset:1920
	global_store_dword v[66:67], v14, off
	global_store_dword v[66:67], v62, off offset:128
	global_store_dword v[66:67], v46, off offset:256
	global_store_dword v[66:67], v30, off offset:384
	global_store_dword v[66:67], v15, off offset:512
	global_store_dword v[66:67], v63, off offset:640
	global_store_dword v[66:67], v47, off offset:768
	global_store_dword v[66:67], v31, off offset:896
	global_store_dword v[66:67], v16, off offset:1024
	global_store_dword v[66:67], v64, off offset:1152
	global_store_dword v[66:67], v48, off offset:1280
	global_store_dword v[66:67], v32, off offset:1408
	global_store_dword v[66:67], v17, off offset:1536
	global_store_dword v[66:67], v65, off offset:1664
	global_store_dword v[66:67], v49, off offset:1792
	global_store_dword v[66:67], v33, off offset:1920
	s_and_saveexec_b64 s[36:37], vcc
	s_cbranch_execz .LBB0_834
	s_lshl_b64 s[0:1], s[0:1], 11
	s_mov_b64 s[10:11], s[8:9]
	v_or_b32_e32 v0, s4, v226
	s_add_u32 s0, s10, s0
	v_lshlrev_b32_e32 v66, 1, v0
	s_addc_u32 s1, s11, s1
	v_ashrrev_i32_e32 v67, 31, v66
	v_lshl_add_u64 v[66:67], v[66:67], 2, s[0:1]
	global_store_dwordx2 v[66:67], v[198:199], off
